# v69 + lever 4 on the leading half: static s_setprio 1 for the wr==0 waves over each K-loop
# speedup vs baseline: 1.0048x; 1.0048x over previous
;     __host__ __device__ bool next(int i, Unit& u) const { const int P = (i >> 1) * G + c; if (P >= 256) return false; u.pm = P >> 3; u.pn = (P & 7) + 8 * (i & 1); return true; }
; template <class Epi, class Sched, bool ALIGN_EPI = false, bool SP2 = false>
; __device__ __forceinline__ void gemm_phase(PG8_LAS unsigned char* lds, const Gemm g, const Sched& S, const Epi& E, const int wv) {
;     ...
;         const bool has_next = S.next(ui + 1, nxt);
;         const char* nA = has_next ? (const char*)g.A + (size_t)nxt.pm * tstepA + (g.amod ? (size_t)(nxt.pn % g.amod) * K * 2 : (size_t)0) : cA; const char* nB = has_next ? (const char*)g.Bt + (size_t)nxt.pn * tstepB : cB;
;         for (int t = 0; t < nt; t += 2) {
;             const bool last = (t == nt - 2);
;             const char* a1 = cA + (size_t)(t + 1) * kstep;
;             const char* a2 = last ? nA : cA + (size_t)(t + 2) * kstep; const char* b2 = last ? nB : cB + (size_t)(t + 2) * kstep;
;             const char* a3 = a2 + kstep; const char* b3 = b2 + kstep;
;     ...
; #pragma unroll
;         for (int a = 0; a < 2; ++a)
; #pragma unroll
;             for (int b = 0; b < 2; ++b)
; #pragma unroll
;                 for (int m = 0; m < 4; ++m)
; #pragma unroll
;                     for (int n = 0; n < 2; ++n) acc[a][b][m][n] = (f32x4){0.f, 0.f, 0.f, 0.f};
.LBB0_174:
	s_ashr_i32 s35, s34, 31
	s_lshl_b64 s[46:47], s[34:35], 20
	s_add_u32 s46, s51, s46
	v_mov_b32_e32 v153, 0
	s_addc_u32 s47, s52, s47
	s_andn2_b64 vcc, exec, s[28:29]
	v_mov_b32_e32 v152, v153
	v_pk_mov_b32 v[150:151], v[152:153], v[152:153]
	v_pk_mov_b32 v[148:149], v[152:153], v[152:153]
	v_pk_mov_b32 v[146:147], v[152:153], v[152:153]
	v_pk_mov_b32 v[136:137], v[152:153], v[152:153]
	v_pk_mov_b32 v[134:135], v[152:153], v[152:153]
	v_pk_mov_b32 v[132:133], v[152:153], v[152:153]
	v_pk_mov_b32 v[130:131], v[152:153], v[152:153]
	v_pk_mov_b32 v[120:121], v[152:153], v[152:153]
	v_pk_mov_b32 v[118:119], v[152:153], v[152:153]
	v_pk_mov_b32 v[116:117], v[152:153], v[152:153]
	v_pk_mov_b32 v[114:115], v[152:153], v[152:153]
	v_pk_mov_b32 v[104:105], v[152:153], v[152:153]
	v_pk_mov_b32 v[102:103], v[152:153], v[152:153]
	v_pk_mov_b32 v[100:101], v[152:153], v[152:153]
	v_pk_mov_b32 v[98:99], v[152:153], v[152:153]
	v_pk_mov_b32 v[144:145], v[152:153], v[152:153]
	v_pk_mov_b32 v[142:143], v[152:153], v[152:153]
	v_pk_mov_b32 v[140:141], v[152:153], v[152:153]
	v_pk_mov_b32 v[138:139], v[152:153], v[152:153]
	v_pk_mov_b32 v[128:129], v[152:153], v[152:153]
	v_pk_mov_b32 v[126:127], v[152:153], v[152:153]
	v_pk_mov_b32 v[124:125], v[152:153], v[152:153]
	v_pk_mov_b32 v[122:123], v[152:153], v[152:153]
	v_pk_mov_b32 v[112:113], v[152:153], v[152:153]
	v_pk_mov_b32 v[110:111], v[152:153], v[152:153]
	v_pk_mov_b32 v[108:109], v[152:153], v[152:153]
	v_pk_mov_b32 v[106:107], v[152:153], v[152:153]
	v_pk_mov_b32 v[96:97], v[152:153], v[152:153]
	v_pk_mov_b32 v[94:95], v[152:153], v[152:153]
	v_pk_mov_b32 v[92:93], v[152:153], v[152:153]
	v_pk_mov_b32 v[90:91], v[152:153], v[152:153]
	v_pk_mov_b32 v[80:81], v[152:153], v[152:153]
	v_pk_mov_b32 v[78:79], v[152:153], v[152:153]
	v_pk_mov_b32 v[72:73], v[152:153], v[152:153]
	v_pk_mov_b32 v[70:71], v[152:153], v[152:153]
	v_pk_mov_b32 v[48:49], v[152:153], v[152:153]
	v_pk_mov_b32 v[46:47], v[152:153], v[152:153]
	v_pk_mov_b32 v[44:45], v[152:153], v[152:153]
	v_pk_mov_b32 v[42:43], v[152:153], v[152:153]
	v_pk_mov_b32 v[32:33], v[152:153], v[152:153]
	v_pk_mov_b32 v[30:31], v[152:153], v[152:153]
	v_pk_mov_b32 v[28:29], v[152:153], v[152:153]
	v_pk_mov_b32 v[26:27], v[152:153], v[152:153]
	v_pk_mov_b32 v[16:17], v[152:153], v[152:153]
	v_pk_mov_b32 v[14:15], v[152:153], v[152:153]
	v_pk_mov_b32 v[12:13], v[152:153], v[152:153]
	v_pk_mov_b32 v[10:11], v[152:153], v[152:153]
	v_pk_mov_b32 v[64:65], v[152:153], v[152:153]
	v_pk_mov_b32 v[62:63], v[152:153], v[152:153]
	v_pk_mov_b32 v[56:57], v[152:153], v[152:153]
	v_pk_mov_b32 v[54:55], v[152:153], v[152:153]
	v_pk_mov_b32 v[40:41], v[152:153], v[152:153]
	v_pk_mov_b32 v[38:39], v[152:153], v[152:153]
	v_pk_mov_b32 v[36:37], v[152:153], v[152:153]
	v_pk_mov_b32 v[34:35], v[152:153], v[152:153]
	v_pk_mov_b32 v[24:25], v[152:153], v[152:153]
	v_pk_mov_b32 v[22:23], v[152:153], v[152:153]
	v_pk_mov_b32 v[20:21], v[152:153], v[152:153]
	v_pk_mov_b32 v[18:19], v[152:153], v[152:153]
	v_pk_mov_b32 v[8:9], v[152:153], v[152:153]
	v_pk_mov_b32 v[6:7], v[152:153], v[152:153]
	v_pk_mov_b32 v[4:5], v[152:153], v[152:153]
	v_pk_mov_b32 v[2:3], v[152:153], v[152:153]
	s_cbranch_vccnz .LBB0_178
	s_and_b64 s[42:43], s[42:43], exec
	s_cselect_b32 s11, s47, s13
	s_cselect_b32 s35, s46, s12
	s_add_u32 s12, s12, 0x80080
	s_addc_u32 s13, s13, 0
	s_add_u32 s42, s14, 0x100
	v_mov_b32_e32 v2, 0
	s_addc_u32 s43, s15, 0
	s_mov_b32 s14, 0
	v_mov_b32_e32 v3, v2
	v_pk_mov_b32 v[4:5], v[2:3], v[2:3]
	v_pk_mov_b32 v[6:7], v[2:3], v[2:3]
	v_pk_mov_b32 v[8:9], v[2:3], v[2:3]
	v_pk_mov_b32 v[18:19], v[2:3], v[2:3]
	v_pk_mov_b32 v[20:21], v[2:3], v[2:3]
	v_pk_mov_b32 v[22:23], v[2:3], v[2:3]
	v_pk_mov_b32 v[24:25], v[2:3], v[2:3]
	v_pk_mov_b32 v[34:35], v[2:3], v[2:3]
	v_pk_mov_b32 v[36:37], v[2:3], v[2:3]
	v_pk_mov_b32 v[38:39], v[2:3], v[2:3]
	v_pk_mov_b32 v[40:41], v[2:3], v[2:3]
	v_pk_mov_b32 v[54:55], v[2:3], v[2:3]
	v_pk_mov_b32 v[56:57], v[2:3], v[2:3]
	v_pk_mov_b32 v[62:63], v[2:3], v[2:3]
	v_pk_mov_b32 v[64:65], v[2:3], v[2:3]
	v_pk_mov_b32 v[10:11], v[2:3], v[2:3]
	v_pk_mov_b32 v[12:13], v[2:3], v[2:3]
	v_pk_mov_b32 v[14:15], v[2:3], v[2:3]
	v_pk_mov_b32 v[16:17], v[2:3], v[2:3]
	v_pk_mov_b32 v[26:27], v[2:3], v[2:3]
	v_pk_mov_b32 v[28:29], v[2:3], v[2:3]
	v_pk_mov_b32 v[30:31], v[2:3], v[2:3]
	v_pk_mov_b32 v[32:33], v[2:3], v[2:3]
	v_pk_mov_b32 v[42:43], v[2:3], v[2:3]
	v_pk_mov_b32 v[44:45], v[2:3], v[2:3]
	v_pk_mov_b32 v[46:47], v[2:3], v[2:3]
	v_pk_mov_b32 v[48:49], v[2:3], v[2:3]
	v_pk_mov_b32 v[70:71], v[2:3], v[2:3]
	v_pk_mov_b32 v[72:73], v[2:3], v[2:3]
	v_pk_mov_b32 v[78:79], v[2:3], v[2:3]
	v_pk_mov_b32 v[80:81], v[2:3], v[2:3]
	v_pk_mov_b32 v[90:91], v[2:3], v[2:3]
	v_pk_mov_b32 v[92:93], v[2:3], v[2:3]
	v_pk_mov_b32 v[94:95], v[2:3], v[2:3]
	v_pk_mov_b32 v[96:97], v[2:3], v[2:3]
	v_pk_mov_b32 v[106:107], v[2:3], v[2:3]
	v_pk_mov_b32 v[108:109], v[2:3], v[2:3]
	v_pk_mov_b32 v[110:111], v[2:3], v[2:3]
	v_pk_mov_b32 v[112:113], v[2:3], v[2:3]
	v_pk_mov_b32 v[122:123], v[2:3], v[2:3]
	v_pk_mov_b32 v[124:125], v[2:3], v[2:3]
	v_pk_mov_b32 v[126:127], v[2:3], v[2:3]
	v_pk_mov_b32 v[128:129], v[2:3], v[2:3]
	v_pk_mov_b32 v[138:139], v[2:3], v[2:3]
	v_pk_mov_b32 v[140:141], v[2:3], v[2:3]
	v_pk_mov_b32 v[142:143], v[2:3], v[2:3]
	v_pk_mov_b32 v[144:145], v[2:3], v[2:3]
	v_pk_mov_b32 v[98:99], v[2:3], v[2:3]
	v_pk_mov_b32 v[100:101], v[2:3], v[2:3]
	v_pk_mov_b32 v[102:103], v[2:3], v[2:3]
	v_pk_mov_b32 v[104:105], v[2:3], v[2:3]
	v_pk_mov_b32 v[114:115], v[2:3], v[2:3]
	v_pk_mov_b32 v[116:117], v[2:3], v[2:3]
	v_pk_mov_b32 v[118:119], v[2:3], v[2:3]
	v_pk_mov_b32 v[120:121], v[2:3], v[2:3]
	v_pk_mov_b32 v[130:131], v[2:3], v[2:3]
	v_pk_mov_b32 v[132:133], v[2:3], v[2:3]
	v_pk_mov_b32 v[134:135], v[2:3], v[2:3]
	v_pk_mov_b32 v[136:137], v[2:3], v[2:3]
	v_pk_mov_b32 v[146:147], v[2:3], v[2:3]
	v_pk_mov_b32 v[148:149], v[2:3], v[2:3]
	v_pk_mov_b32 v[150:151], v[2:3], v[2:3]
	v_pk_mov_b32 v[152:153], v[2:3], v[2:3]
	v_add_u32_e32 v171, 0x10000, v185
	v_add_u32_e32 v173, 0x14000, v185
	v_add_u32_e32 v201, 0x18000, v185
	v_add_u32_e32 v227, 0x1c000, v185
	v_add_u32_e32 v59, 0x80000, v162
	v_add_u32_e32 v246, 0x80000, v164
	s_cmp_eq_u64 s[30:31], 0
	s_cbranch_scc1 .Lsp_skip_0
	s_setprio 1

;     __host__ __device__ bool next(int i, Unit& u) const { const int P = (i >> 1) * G + c; if (P >= 256) return false; u.pm = P >> 3; u.pn = (P & 7) + 8 * (i & 1); return true; }
; template <class Epi, class Sched, bool ALIGN_EPI = false, bool SP2 = false>
; __device__ __forceinline__ void gemm_phase(PG8_LAS unsigned char* lds, const Gemm g, const Sched& S, const Epi& E, const int wv) {
;     ...
;         const bool has_next = S.next(ui + 1, nxt);
;         const char* nA = has_next ? (const char*)g.A + (size_t)nxt.pm * tstepA + (g.amod ? (size_t)(nxt.pn % g.amod) * K * 2 : (size_t)0) : cA; const char* nB = has_next ? (const char*)g.Bt + (size_t)nxt.pn * tstepB : cB;
;         for (int t = 0; t < nt; t += 2) {
;             const bool last = (t == nt - 2);
;             const char* a1 = cA + (size_t)(t + 1) * kstep;
;             const char* a2 = last ? nA : cA + (size_t)(t + 2) * kstep; const char* b2 = last ? nB : cB + (size_t)(t + 2) * kstep;
;             const char* a3 = a2 + kstep; const char* b3 = b2 + kstep;
;     ...
; #pragma unroll
;         for (int a = 0; a < 2; ++a)
; #pragma unroll
;             for (int b = 0; b < 2; ++b)
; #pragma unroll
;                 for (int m = 0; m < 4; ++m)
; #pragma unroll
;                     for (int n = 0; n < 2; ++n) acc[a][b][m][n] = (f32x4){0.f, 0.f, 0.f, 0.f};
.LBB0_334:
	v_mov_b32_e32 v141, 0
	s_andn2_b64 vcc, exec, s[34:35]
	v_mov_b32_e32 v140, v141
	v_pk_mov_b32 v[138:139], v[140:141], v[140:141]
	v_pk_mov_b32 v[144:145], v[140:141], v[140:141]
	v_pk_mov_b32 v[142:143], v[140:141], v[140:141]
	v_pk_mov_b32 v[128:129], v[140:141], v[140:141]
	v_pk_mov_b32 v[126:127], v[140:141], v[140:141]
	v_pk_mov_b32 v[124:125], v[140:141], v[140:141]
	v_pk_mov_b32 v[122:123], v[140:141], v[140:141]
	v_pk_mov_b32 v[112:113], v[140:141], v[140:141]
	v_pk_mov_b32 v[110:111], v[140:141], v[140:141]
	v_pk_mov_b32 v[108:109], v[140:141], v[140:141]
	v_pk_mov_b32 v[106:107], v[140:141], v[140:141]
	v_pk_mov_b32 v[96:97], v[140:141], v[140:141]
	v_pk_mov_b32 v[94:95], v[140:141], v[140:141]
	v_pk_mov_b32 v[92:93], v[140:141], v[140:141]
	v_pk_mov_b32 v[90:91], v[140:141], v[140:141]
	v_pk_mov_b32 v[136:137], v[140:141], v[140:141]
	v_pk_mov_b32 v[134:135], v[140:141], v[140:141]
	v_pk_mov_b32 v[132:133], v[140:141], v[140:141]
	v_pk_mov_b32 v[130:131], v[140:141], v[140:141]
	v_pk_mov_b32 v[120:121], v[140:141], v[140:141]
	v_pk_mov_b32 v[118:119], v[140:141], v[140:141]
	v_pk_mov_b32 v[116:117], v[140:141], v[140:141]
	v_pk_mov_b32 v[114:115], v[140:141], v[140:141]
	v_pk_mov_b32 v[104:105], v[140:141], v[140:141]
	v_pk_mov_b32 v[102:103], v[140:141], v[140:141]
	v_pk_mov_b32 v[100:101], v[140:141], v[140:141]
	v_pk_mov_b32 v[98:99], v[140:141], v[140:141]
	v_pk_mov_b32 v[88:89], v[140:141], v[140:141]
	v_pk_mov_b32 v[86:87], v[140:141], v[140:141]
	v_pk_mov_b32 v[84:85], v[140:141], v[140:141]
	v_pk_mov_b32 v[82:83], v[140:141], v[140:141]
	v_pk_mov_b32 v[80:81], v[140:141], v[140:141]
	v_pk_mov_b32 v[78:79], v[140:141], v[140:141]
	v_pk_mov_b32 v[76:77], v[140:141], v[140:141]
	v_pk_mov_b32 v[74:75], v[140:141], v[140:141]
	v_pk_mov_b32 v[64:65], v[140:141], v[140:141]
	v_pk_mov_b32 v[62:63], v[140:141], v[140:141]
	v_pk_mov_b32 v[60:61], v[140:141], v[140:141]
	v_pk_mov_b32 v[58:59], v[140:141], v[140:141]
	s_nop 0
	v_pk_mov_b32 v[40:41], v[140:141], v[140:141]
	v_pk_mov_b32 v[38:39], v[140:141], v[140:141]
	v_pk_mov_b32 v[36:37], v[140:141], v[140:141]
	v_pk_mov_b32 v[34:35], v[140:141], v[140:141]
	v_pk_mov_b32 v[16:17], v[140:141], v[140:141]
	v_pk_mov_b32 v[14:15], v[140:141], v[140:141]
	v_pk_mov_b32 v[12:13], v[140:141], v[140:141]
	v_pk_mov_b32 v[10:11], v[140:141], v[140:141]
	v_pk_mov_b32 v[72:73], v[140:141], v[140:141]
	v_pk_mov_b32 v[70:71], v[140:141], v[140:141]
	v_pk_mov_b32 v[68:69], v[140:141], v[140:141]
	v_pk_mov_b32 v[66:67], v[140:141], v[140:141]
	v_pk_mov_b32 v[56:57], v[140:141], v[140:141]
	v_pk_mov_b32 v[54:55], v[140:141], v[140:141]
	v_pk_mov_b32 v[52:53], v[140:141], v[140:141]
	v_pk_mov_b32 v[50:51], v[140:141], v[140:141]
	v_pk_mov_b32 v[24:25], v[140:141], v[140:141]
	v_pk_mov_b32 v[22:23], v[140:141], v[140:141]
	v_pk_mov_b32 v[20:21], v[140:141], v[140:141]
	v_pk_mov_b32 v[18:19], v[140:141], v[140:141]
	v_pk_mov_b32 v[8:9], v[140:141], v[140:141]
	v_pk_mov_b32 v[6:7], v[140:141], v[140:141]
	v_pk_mov_b32 v[4:5], v[140:141], v[140:141]
	v_pk_mov_b32 v[2:3], v[140:141], v[140:141]
	s_cbranch_vccnz .LBB0_337
	s_add_u32 s12, s40, 0x80080
	s_addc_u32 s13, s41, 0
	s_add_u32 s11, s14, 0x100
	v_mov_b32_e32 v2, 0
	s_addc_u32 s17, s15, 0
	s_mov_b32 s14, 0
	v_mov_b32_e32 v3, v2
	v_pk_mov_b32 v[4:5], v[2:3], v[2:3]
	v_pk_mov_b32 v[6:7], v[2:3], v[2:3]
	v_pk_mov_b32 v[8:9], v[2:3], v[2:3]
	v_pk_mov_b32 v[18:19], v[2:3], v[2:3]
	v_pk_mov_b32 v[20:21], v[2:3], v[2:3]
	v_pk_mov_b32 v[22:23], v[2:3], v[2:3]
	v_pk_mov_b32 v[24:25], v[2:3], v[2:3]
	v_pk_mov_b32 v[50:51], v[2:3], v[2:3]
	v_pk_mov_b32 v[52:53], v[2:3], v[2:3]
	v_pk_mov_b32 v[54:55], v[2:3], v[2:3]
	v_pk_mov_b32 v[56:57], v[2:3], v[2:3]
	v_pk_mov_b32 v[66:67], v[2:3], v[2:3]
	v_pk_mov_b32 v[68:69], v[2:3], v[2:3]
	v_pk_mov_b32 v[70:71], v[2:3], v[2:3]
	v_pk_mov_b32 v[72:73], v[2:3], v[2:3]
	v_pk_mov_b32 v[10:11], v[2:3], v[2:3]
	v_pk_mov_b32 v[12:13], v[2:3], v[2:3]
	v_pk_mov_b32 v[14:15], v[2:3], v[2:3]
	v_pk_mov_b32 v[16:17], v[2:3], v[2:3]
	v_pk_mov_b32 v[34:35], v[2:3], v[2:3]
	v_pk_mov_b32 v[36:37], v[2:3], v[2:3]
	v_pk_mov_b32 v[38:39], v[2:3], v[2:3]
	v_pk_mov_b32 v[40:41], v[2:3], v[2:3]
	v_pk_mov_b32 v[58:59], v[2:3], v[2:3]
	v_pk_mov_b32 v[60:61], v[2:3], v[2:3]
	v_pk_mov_b32 v[62:63], v[2:3], v[2:3]
	v_pk_mov_b32 v[64:65], v[2:3], v[2:3]
	v_pk_mov_b32 v[74:75], v[2:3], v[2:3]
	v_pk_mov_b32 v[76:77], v[2:3], v[2:3]
	v_pk_mov_b32 v[78:79], v[2:3], v[2:3]
	v_pk_mov_b32 v[80:81], v[2:3], v[2:3]
	v_pk_mov_b32 v[82:83], v[2:3], v[2:3]
	v_pk_mov_b32 v[84:85], v[2:3], v[2:3]
	v_pk_mov_b32 v[86:87], v[2:3], v[2:3]
	v_pk_mov_b32 v[88:89], v[2:3], v[2:3]
	v_pk_mov_b32 v[98:99], v[2:3], v[2:3]
	v_pk_mov_b32 v[100:101], v[2:3], v[2:3]
	v_pk_mov_b32 v[102:103], v[2:3], v[2:3]
	v_pk_mov_b32 v[104:105], v[2:3], v[2:3]
	v_pk_mov_b32 v[114:115], v[2:3], v[2:3]
	v_pk_mov_b32 v[116:117], v[2:3], v[2:3]
	v_pk_mov_b32 v[118:119], v[2:3], v[2:3]
	v_pk_mov_b32 v[120:121], v[2:3], v[2:3]
	v_pk_mov_b32 v[130:131], v[2:3], v[2:3]
	v_pk_mov_b32 v[132:133], v[2:3], v[2:3]
	v_pk_mov_b32 v[134:135], v[2:3], v[2:3]
	v_pk_mov_b32 v[136:137], v[2:3], v[2:3]
	v_pk_mov_b32 v[90:91], v[2:3], v[2:3]
	v_pk_mov_b32 v[92:93], v[2:3], v[2:3]
	v_pk_mov_b32 v[94:95], v[2:3], v[2:3]
	v_pk_mov_b32 v[96:97], v[2:3], v[2:3]
	v_pk_mov_b32 v[106:107], v[2:3], v[2:3]
	v_pk_mov_b32 v[108:109], v[2:3], v[2:3]
	v_pk_mov_b32 v[110:111], v[2:3], v[2:3]
	v_pk_mov_b32 v[112:113], v[2:3], v[2:3]
	v_pk_mov_b32 v[122:123], v[2:3], v[2:3]
	v_pk_mov_b32 v[124:125], v[2:3], v[2:3]
	v_pk_mov_b32 v[126:127], v[2:3], v[2:3]
	v_pk_mov_b32 v[128:129], v[2:3], v[2:3]
	v_pk_mov_b32 v[142:143], v[2:3], v[2:3]
	v_pk_mov_b32 v[144:145], v[2:3], v[2:3]
	v_pk_mov_b32 v[138:139], v[2:3], v[2:3]
	v_pk_mov_b32 v[140:141], v[2:3], v[2:3]
	v_add_u32_e32 v171, 0x10000, v197
	v_add_u32_e32 v227, 0x14000, v197
	v_add_u32_e32 v244, 0x18000, v197
	v_add_u32_e32 v245, 0x1c000, v197
	v_add_u32_e32 v246, 0x80000, v166
	v_add_u32_e32 v247, 0x80000, v164
	s_cmp_eq_u64 s[42:43], 0
	s_cbranch_scc1 .Lsp_skip_1
	s_setprio 1

; template <class Epi, class Sched, bool ALIGN_EPI = false, bool SP2 = false>
; __device__ __forceinline__ void gemm_phase(PG8_LAS unsigned char* lds, const Gemm g, const Sched& S, const Epi& E, const int wv) {
;     ...
;         const char* nA = has_next ? (const char*)g.A + (size_t)nxt.pm * tstepA + (g.amod ? (size_t)(nxt.pn % g.amod) * K * 2 : (size_t)0) : cA; const char* nB = has_next ? (const char*)g.Bt + (size_t)nxt.pn * tstepB : cB;
;         for (int t = 0; t < nt; t += 2) {
;     ...
; #pragma unroll
;         for (int a = 0; a < 2; ++a)
; #pragma unroll
;             for (int b = 0; b < 2; ++b)
; #pragma unroll
;                 for (int m = 0; m < 4; ++m)
; #pragma unroll
;                     for (int n = 0; n < 2; ++n) acc[a][b][m][n] = (f32x4){0.f, 0.f, 0.f, 0.f};
;         cur = nxt; cA = nA; cB = nB; ++ui;
.LBB0_698:
	s_and_b64 s[44:45], s[44:45], exec
	s_cselect_b32 s31, s15, s55
	s_cselect_b32 s71, s14, s54
	s_add_u32 s44, s54, 0x80080
	s_addc_u32 s45, s55, 0
	s_add_u32 s56, s56, 0x100
	v_mov_b32_e32 v2, 0
	s_addc_u32 s57, s57, 0
	s_mov_b32 s54, 0
	v_mov_b32_e32 v3, v2
	v_pk_mov_b32 v[4:5], v[2:3], v[2:3]
	v_pk_mov_b32 v[6:7], v[2:3], v[2:3]
	v_pk_mov_b32 v[8:9], v[2:3], v[2:3]
	v_pk_mov_b32 v[18:19], v[2:3], v[2:3]
	v_pk_mov_b32 v[20:21], v[2:3], v[2:3]
	v_pk_mov_b32 v[22:23], v[2:3], v[2:3]
	v_pk_mov_b32 v[24:25], v[2:3], v[2:3]
	v_pk_mov_b32 v[34:35], v[2:3], v[2:3]
	v_pk_mov_b32 v[36:37], v[2:3], v[2:3]
	v_pk_mov_b32 v[38:39], v[2:3], v[2:3]
	v_pk_mov_b32 v[40:41], v[2:3], v[2:3]
	v_pk_mov_b32 v[50:51], v[2:3], v[2:3]
	v_pk_mov_b32 v[52:53], v[2:3], v[2:3]
	v_pk_mov_b32 v[54:55], v[2:3], v[2:3]
	v_pk_mov_b32 v[56:57], v[2:3], v[2:3]
	v_pk_mov_b32 v[10:11], v[2:3], v[2:3]
	v_pk_mov_b32 v[12:13], v[2:3], v[2:3]
	v_pk_mov_b32 v[14:15], v[2:3], v[2:3]
	v_pk_mov_b32 v[16:17], v[2:3], v[2:3]
	v_pk_mov_b32 v[26:27], v[2:3], v[2:3]
	v_pk_mov_b32 v[28:29], v[2:3], v[2:3]
	v_pk_mov_b32 v[30:31], v[2:3], v[2:3]
	v_pk_mov_b32 v[32:33], v[2:3], v[2:3]
	v_pk_mov_b32 v[42:43], v[2:3], v[2:3]
	v_pk_mov_b32 v[44:45], v[2:3], v[2:3]
	v_pk_mov_b32 v[46:47], v[2:3], v[2:3]
	v_pk_mov_b32 v[48:49], v[2:3], v[2:3]
	v_pk_mov_b32 v[58:59], v[2:3], v[2:3]
	v_pk_mov_b32 v[60:61], v[2:3], v[2:3]
	v_pk_mov_b32 v[62:63], v[2:3], v[2:3]
	v_pk_mov_b32 v[64:65], v[2:3], v[2:3]
	v_pk_mov_b32 v[66:67], v[2:3], v[2:3]
	v_pk_mov_b32 v[68:69], v[2:3], v[2:3]
	v_pk_mov_b32 v[70:71], v[2:3], v[2:3]
	v_pk_mov_b32 v[72:73], v[2:3], v[2:3]
	v_pk_mov_b32 v[82:83], v[2:3], v[2:3]
	v_pk_mov_b32 v[84:85], v[2:3], v[2:3]
	v_pk_mov_b32 v[86:87], v[2:3], v[2:3]
	v_pk_mov_b32 v[88:89], v[2:3], v[2:3]
	v_pk_mov_b32 v[98:99], v[2:3], v[2:3]
	v_pk_mov_b32 v[100:101], v[2:3], v[2:3]
	v_pk_mov_b32 v[102:103], v[2:3], v[2:3]
	v_pk_mov_b32 v[104:105], v[2:3], v[2:3]
	v_pk_mov_b32 v[118:119], v[2:3], v[2:3]
	v_pk_mov_b32 v[120:121], v[2:3], v[2:3]
	v_pk_mov_b32 v[122:123], v[2:3], v[2:3]
	v_pk_mov_b32 v[124:125], v[2:3], v[2:3]
	v_pk_mov_b32 v[74:75], v[2:3], v[2:3]
	v_pk_mov_b32 v[76:77], v[2:3], v[2:3]
	v_pk_mov_b32 v[78:79], v[2:3], v[2:3]
	v_pk_mov_b32 v[80:81], v[2:3], v[2:3]
	v_pk_mov_b32 v[90:91], v[2:3], v[2:3]
	v_pk_mov_b32 v[92:93], v[2:3], v[2:3]
	v_pk_mov_b32 v[94:95], v[2:3], v[2:3]
	v_pk_mov_b32 v[96:97], v[2:3], v[2:3]
	v_pk_mov_b32 v[106:107], v[2:3], v[2:3]
	v_pk_mov_b32 v[108:109], v[2:3], v[2:3]
	v_pk_mov_b32 v[110:111], v[2:3], v[2:3]
	v_pk_mov_b32 v[112:113], v[2:3], v[2:3]
	v_pk_mov_b32 v[130:131], v[2:3], v[2:3]
	v_pk_mov_b32 v[132:133], v[2:3], v[2:3]
	v_pk_mov_b32 v[134:135], v[2:3], v[2:3]
	v_pk_mov_b32 v[136:137], v[2:3], v[2:3]
	v_add_u32_e32 v190, 0x10000, v230
	v_add_u32_e32 v191, 0x14000, v230
	v_add_u32_e32 v192, 0x18000, v230
	v_add_u32_e32 v193, 0x1c000, v230
	v_add_u32_e32 v115, 0x80000, v194
	v_add_u32_e32 v201, 0x80000, v196
	s_cmp_eq_u64 s[48:49], 0
	s_cbranch_scc1 .Lsp_skip_2
	s_setprio 1

; template <class Epi, class Sched, bool ALIGN_EPI = false, bool SP2 = false>
; __device__ __forceinline__ void gemm_phase(PG8_LAS unsigned char* lds, const Gemm g, const Sched& S, const Epi& E, const int wv) {
;     ...
;         const char* nA = has_next ? (const char*)g.A + (size_t)nxt.pm * tstepA + (g.amod ? (size_t)(nxt.pn % g.amod) * K * 2 : (size_t)0) : cA; const char* nB = has_next ? (const char*)g.Bt + (size_t)nxt.pn * tstepB : cB;
;         for (int t = 0; t < nt; t += 2) {
;     ...
; #pragma unroll
;         for (int a = 0; a < 2; ++a)
; #pragma unroll
;             for (int b = 0; b < 2; ++b)
; #pragma unroll
;                 for (int m = 0; m < 4; ++m)
; #pragma unroll
;                     for (int n = 0; n < 2; ++n) acc[a][b][m][n] = (f32x4){0.f, 0.f, 0.f, 0.f};
;         cur = nxt; cA = nA; cB = nB; ++ui;
.LBB0_808:
	s_and_b64 s[14:15], s[46:47], exec
	s_cselect_b32 s11, s91, s49
	s_cselect_b32 s13, s90, s48
	s_add_u32 s35, s52, 0x100
	v_mov_b32_e32 v18, 0
	s_addc_u32 s51, s53, 0
	s_mov_b32 s46, 0
	v_mov_b32_e32 v19, v18
	v_pk_mov_b32 v[20:21], v[18:19], v[18:19]
	v_pk_mov_b32 v[90:91], v[18:19], v[18:19]
	v_pk_mov_b32 v[92:93], v[18:19], v[18:19]
	v_pk_mov_b32 v[22:23], v[18:19], v[18:19]
	v_pk_mov_b32 v[24:25], v[18:19], v[18:19]
	v_pk_mov_b32 v[94:95], v[18:19], v[18:19]
	v_pk_mov_b32 v[96:97], v[18:19], v[18:19]
	v_pk_mov_b32 v[2:3], v[18:19], v[18:19]
	v_pk_mov_b32 v[4:5], v[18:19], v[18:19]
	v_pk_mov_b32 v[66:67], v[18:19], v[18:19]
	v_pk_mov_b32 v[68:69], v[18:19], v[18:19]
	v_pk_mov_b32 v[10:11], v[18:19], v[18:19]
	v_pk_mov_b32 v[12:13], v[18:19], v[18:19]
	v_pk_mov_b32 v[82:83], v[18:19], v[18:19]
	v_pk_mov_b32 v[84:85], v[18:19], v[18:19]
	v_pk_mov_b32 v[26:27], v[18:19], v[18:19]
	v_pk_mov_b32 v[28:29], v[18:19], v[18:19]
	v_pk_mov_b32 v[98:99], v[18:19], v[18:19]
	v_pk_mov_b32 v[100:101], v[18:19], v[18:19]
	v_pk_mov_b32 v[30:31], v[18:19], v[18:19]
	v_pk_mov_b32 v[32:33], v[18:19], v[18:19]
	v_pk_mov_b32 v[102:103], v[18:19], v[18:19]
	v_pk_mov_b32 v[104:105], v[18:19], v[18:19]
	v_pk_mov_b32 v[6:7], v[18:19], v[18:19]
	v_pk_mov_b32 v[8:9], v[18:19], v[18:19]
	v_pk_mov_b32 v[70:71], v[18:19], v[18:19]
	v_pk_mov_b32 v[72:73], v[18:19], v[18:19]
	v_pk_mov_b32 v[14:15], v[18:19], v[18:19]
	v_pk_mov_b32 v[16:17], v[18:19], v[18:19]
	v_pk_mov_b32 v[86:87], v[18:19], v[18:19]
	v_pk_mov_b32 v[88:89], v[18:19], v[18:19]
	v_pk_mov_b32 v[50:51], v[18:19], v[18:19]
	v_pk_mov_b32 v[52:53], v[18:19], v[18:19]
	v_pk_mov_b32 v[122:123], v[18:19], v[18:19]
	v_pk_mov_b32 v[124:125], v[18:19], v[18:19]
	v_pk_mov_b32 v[54:55], v[18:19], v[18:19]
	v_pk_mov_b32 v[56:57], v[18:19], v[18:19]
	v_pk_mov_b32 v[126:127], v[18:19], v[18:19]
	v_pk_mov_b32 v[128:129], v[18:19], v[18:19]
	v_pk_mov_b32 v[34:35], v[18:19], v[18:19]
	v_pk_mov_b32 v[36:37], v[18:19], v[18:19]
	v_pk_mov_b32 v[106:107], v[18:19], v[18:19]
	v_pk_mov_b32 v[108:109], v[18:19], v[18:19]
	v_pk_mov_b32 v[42:43], v[18:19], v[18:19]
	v_pk_mov_b32 v[44:45], v[18:19], v[18:19]
	v_pk_mov_b32 v[114:115], v[18:19], v[18:19]
	v_pk_mov_b32 v[116:117], v[18:19], v[18:19]
	v_pk_mov_b32 v[58:59], v[18:19], v[18:19]
	v_pk_mov_b32 v[60:61], v[18:19], v[18:19]
	v_pk_mov_b32 v[130:131], v[18:19], v[18:19]
	v_pk_mov_b32 v[132:133], v[18:19], v[18:19]
	v_pk_mov_b32 v[62:63], v[18:19], v[18:19]
	v_pk_mov_b32 v[64:65], v[18:19], v[18:19]
	v_pk_mov_b32 v[134:135], v[18:19], v[18:19]
	v_pk_mov_b32 v[136:137], v[18:19], v[18:19]
	v_pk_mov_b32 v[38:39], v[18:19], v[18:19]
	v_pk_mov_b32 v[40:41], v[18:19], v[18:19]
	v_pk_mov_b32 v[110:111], v[18:19], v[18:19]
	v_pk_mov_b32 v[112:113], v[18:19], v[18:19]
	v_pk_mov_b32 v[46:47], v[18:19], v[18:19]
	v_pk_mov_b32 v[48:49], v[18:19], v[18:19]
	v_pk_mov_b32 v[118:119], v[18:19], v[18:19]
	v_pk_mov_b32 v[120:121], v[18:19], v[18:19]
	v_add_u32_e32 v192, 0x10000, v208
	v_add_u32_e32 v193, 0x14000, v208
	v_add_u32_e32 v213, 0x18000, v208
	v_add_u32_e32 v227, 0x1c000, v208
	v_add_u32_e32 v218, 0x80000, v170
	v_add_u32_e32 v219, 0x80000, v172
	s_cmp_eq_u64 s[30:31], 0
	s_cbranch_scc1 .Lsp_skip_3
	s_setprio 1

; template <class Epi, class Sched, bool ALIGN_EPI = false, bool SP2 = false>
; __device__ __forceinline__ void gemm_phase(PG8_LAS unsigned char* lds, const Gemm g, const Sched& S, const Epi& E, const int wv) {
;     ...
; #pragma unroll
;         for (int a = 0; a < 2; ++a)
; #pragma unroll
;             for (int b = 0; b < 2; ++b)
; #pragma unroll
;                 for (int m = 0; m < 4; ++m)
; #pragma unroll
;                     for (int n = 0; n < 2; ++n) acc[a][b][m][n] = (f32x4){0.f, 0.f, 0.f, 0.f};
;         cur = nxt; cA = nA; cB = nB; ++ui;
.LBB0_989:
	s_add_u32 s65, s34, 0x100
	v_mov_b32_e32 v2, 0
	s_addc_u32 s66, s35, 0
	s_mov_b32 s44, 0
	v_mov_b32_e32 v3, v2
	v_pk_mov_b32 v[4:5], v[2:3], v[2:3]
	v_pk_mov_b32 v[6:7], v[2:3], v[2:3]
	v_pk_mov_b32 v[8:9], v[2:3], v[2:3]
	v_pk_mov_b32 v[18:19], v[2:3], v[2:3]
	v_pk_mov_b32 v[20:21], v[2:3], v[2:3]
	v_pk_mov_b32 v[22:23], v[2:3], v[2:3]
	v_pk_mov_b32 v[24:25], v[2:3], v[2:3]
	v_pk_mov_b32 v[34:35], v[2:3], v[2:3]
	v_pk_mov_b32 v[36:37], v[2:3], v[2:3]
	v_pk_mov_b32 v[38:39], v[2:3], v[2:3]
	v_pk_mov_b32 v[40:41], v[2:3], v[2:3]
	v_pk_mov_b32 v[50:51], v[2:3], v[2:3]
	v_pk_mov_b32 v[52:53], v[2:3], v[2:3]
	v_pk_mov_b32 v[54:55], v[2:3], v[2:3]
	v_pk_mov_b32 v[56:57], v[2:3], v[2:3]
	v_pk_mov_b32 v[10:11], v[2:3], v[2:3]
	v_pk_mov_b32 v[12:13], v[2:3], v[2:3]
	v_pk_mov_b32 v[14:15], v[2:3], v[2:3]
	v_pk_mov_b32 v[16:17], v[2:3], v[2:3]
	v_pk_mov_b32 v[26:27], v[2:3], v[2:3]
	v_pk_mov_b32 v[28:29], v[2:3], v[2:3]
	v_pk_mov_b32 v[30:31], v[2:3], v[2:3]
	v_pk_mov_b32 v[32:33], v[2:3], v[2:3]
	v_pk_mov_b32 v[42:43], v[2:3], v[2:3]
	v_pk_mov_b32 v[44:45], v[2:3], v[2:3]
	v_pk_mov_b32 v[46:47], v[2:3], v[2:3]
	v_pk_mov_b32 v[48:49], v[2:3], v[2:3]
	v_pk_mov_b32 v[58:59], v[2:3], v[2:3]
	v_pk_mov_b32 v[60:61], v[2:3], v[2:3]
	v_pk_mov_b32 v[62:63], v[2:3], v[2:3]
	v_pk_mov_b32 v[64:65], v[2:3], v[2:3]
	v_pk_mov_b32 v[66:67], v[2:3], v[2:3]
	v_pk_mov_b32 v[68:69], v[2:3], v[2:3]
	v_pk_mov_b32 v[70:71], v[2:3], v[2:3]
	v_pk_mov_b32 v[72:73], v[2:3], v[2:3]
	v_pk_mov_b32 v[82:83], v[2:3], v[2:3]
	v_pk_mov_b32 v[84:85], v[2:3], v[2:3]
	v_pk_mov_b32 v[86:87], v[2:3], v[2:3]
	v_pk_mov_b32 v[88:89], v[2:3], v[2:3]
	v_pk_mov_b32 v[98:99], v[2:3], v[2:3]
	v_pk_mov_b32 v[100:101], v[2:3], v[2:3]
	v_pk_mov_b32 v[102:103], v[2:3], v[2:3]
	v_pk_mov_b32 v[104:105], v[2:3], v[2:3]
	v_pk_mov_b32 v[118:119], v[2:3], v[2:3]
	v_pk_mov_b32 v[120:121], v[2:3], v[2:3]
	v_pk_mov_b32 v[122:123], v[2:3], v[2:3]
	v_pk_mov_b32 v[124:125], v[2:3], v[2:3]
	v_pk_mov_b32 v[74:75], v[2:3], v[2:3]
	v_pk_mov_b32 v[76:77], v[2:3], v[2:3]
	v_pk_mov_b32 v[78:79], v[2:3], v[2:3]
	v_pk_mov_b32 v[80:81], v[2:3], v[2:3]
	v_pk_mov_b32 v[90:91], v[2:3], v[2:3]
	v_pk_mov_b32 v[92:93], v[2:3], v[2:3]
	v_pk_mov_b32 v[94:95], v[2:3], v[2:3]
	v_pk_mov_b32 v[96:97], v[2:3], v[2:3]
	v_pk_mov_b32 v[106:107], v[2:3], v[2:3]
	v_pk_mov_b32 v[108:109], v[2:3], v[2:3]
	v_pk_mov_b32 v[110:111], v[2:3], v[2:3]
	v_pk_mov_b32 v[112:113], v[2:3], v[2:3]
	v_pk_mov_b32 v[130:131], v[2:3], v[2:3]
	v_pk_mov_b32 v[132:133], v[2:3], v[2:3]
	v_pk_mov_b32 v[134:135], v[2:3], v[2:3]
	v_pk_mov_b32 v[136:137], v[2:3], v[2:3]
	v_add_u32_e32 v197, 0x10000, v230
	v_add_u32_e32 v201, 0x14000, v230
	v_add_u32_e32 v203, 0x18000, v230
	v_add_u32_e32 v216, 0x1c000, v230
	s_cmp_eq_u64 s[28:29], 0
	s_cbranch_scc1 .Lsp_skip_4
	s_setprio 1

;     __host__ __device__ bool next(int i, Unit& u) const { const int P = (i >> 1) * G + c; if (P >= 256) return false; u.pm = P >> 3; u.pn = (P & 7) + 8 * (i & 1); return true; }
; template <class Epi, class Sched, bool ALIGN_EPI = false, bool SP2 = false>
; __device__ __forceinline__ void gemm_phase(PG8_LAS unsigned char* lds, const Gemm g, const Sched& S, const Epi& E, const int wv) {
;     ...
;         const bool has_next = S.next(ui + 1, nxt);
;         const char* nA = has_next ? (const char*)g.A + (size_t)nxt.pm * tstepA + (g.amod ? (size_t)(nxt.pn % g.amod) * K * 2 : (size_t)0) : cA; const char* nB = has_next ? (const char*)g.Bt + (size_t)nxt.pn * tstepB : cB;
;         for (int t = 0; t < nt; t += 2) {
;             const bool last = (t == nt - 2);
;             const char* a1 = cA + (size_t)(t + 1) * kstep;
;             const char* a2 = last ? nA : cA + (size_t)(t + 2) * kstep; const char* b2 = last ? nB : cB + (size_t)(t + 2) * kstep;
;             const char* a3 = a2 + kstep; const char* b3 = b2 + kstep;
;     ...
; #pragma unroll
;         for (int a = 0; a < 2; ++a)
; #pragma unroll
;             for (int b = 0; b < 2; ++b)
; #pragma unroll
;                 for (int m = 0; m < 4; ++m)
; #pragma unroll
;                     for (int n = 0; n < 2; ++n) acc[a][b][m][n] = (f32x4){0.f, 0.f, 0.f, 0.f};
.LBB0_1072:
	s_ashr_i32 s17, s16, 31
	s_lshl_b64 s[24:25], s[16:17], 20
	s_add_u32 s24, s43, s24
	v_mov_b32_e32 v133, 0
	s_addc_u32 s25, s44, s25
	s_andn2_b64 vcc, exec, s[12:13]
	v_mov_b32_e32 v132, v133
	v_pk_mov_b32 v[130:131], v[132:133], v[132:133]
	v_pk_mov_b32 v[128:129], v[132:133], v[132:133]
	v_pk_mov_b32 v[126:127], v[132:133], v[132:133]
	v_pk_mov_b32 v[116:117], v[132:133], v[132:133]
	v_pk_mov_b32 v[114:115], v[132:133], v[132:133]
	v_pk_mov_b32 v[112:113], v[132:133], v[132:133]
	v_pk_mov_b32 v[110:111], v[132:133], v[132:133]
	v_pk_mov_b32 v[100:101], v[132:133], v[132:133]
	v_pk_mov_b32 v[98:99], v[132:133], v[132:133]
	s_nop 0
	v_pk_mov_b32 v[96:97], v[132:133], v[132:133]
	v_pk_mov_b32 v[94:95], v[132:133], v[132:133]
	v_pk_mov_b32 v[84:85], v[132:133], v[132:133]
	v_pk_mov_b32 v[82:83], v[132:133], v[132:133]
	v_pk_mov_b32 v[80:81], v[132:133], v[132:133]
	v_pk_mov_b32 v[78:79], v[132:133], v[132:133]
	v_pk_mov_b32 v[124:125], v[132:133], v[132:133]
	v_pk_mov_b32 v[122:123], v[132:133], v[132:133]
	v_pk_mov_b32 v[120:121], v[132:133], v[132:133]
	v_pk_mov_b32 v[118:119], v[132:133], v[132:133]
	v_pk_mov_b32 v[108:109], v[132:133], v[132:133]
	v_pk_mov_b32 v[106:107], v[132:133], v[132:133]
	v_pk_mov_b32 v[104:105], v[132:133], v[132:133]
	v_pk_mov_b32 v[102:103], v[132:133], v[132:133]
	v_pk_mov_b32 v[92:93], v[132:133], v[132:133]
	v_pk_mov_b32 v[90:91], v[132:133], v[132:133]
	v_pk_mov_b32 v[88:89], v[132:133], v[132:133]
	v_pk_mov_b32 v[86:87], v[132:133], v[132:133]
	v_pk_mov_b32 v[76:77], v[132:133], v[132:133]
	v_pk_mov_b32 v[74:75], v[132:133], v[132:133]
	v_pk_mov_b32 v[72:73], v[132:133], v[132:133]
	v_pk_mov_b32 v[70:71], v[132:133], v[132:133]
	v_pk_mov_b32 v[68:69], v[132:133], v[132:133]
	v_pk_mov_b32 v[66:67], v[132:133], v[132:133]
	v_pk_mov_b32 v[64:65], v[132:133], v[132:133]
	v_pk_mov_b32 v[62:63], v[132:133], v[132:133]
	v_pk_mov_b32 v[52:53], v[132:133], v[132:133]
	v_pk_mov_b32 v[50:51], v[132:133], v[132:133]
	v_pk_mov_b32 v[48:49], v[132:133], v[132:133]
	v_pk_mov_b32 v[46:47], v[132:133], v[132:133]
	v_pk_mov_b32 v[36:37], v[132:133], v[132:133]
	v_pk_mov_b32 v[34:35], v[132:133], v[132:133]
	v_pk_mov_b32 v[32:33], v[132:133], v[132:133]
	v_pk_mov_b32 v[30:31], v[132:133], v[132:133]
	v_pk_mov_b32 v[20:21], v[132:133], v[132:133]
	v_pk_mov_b32 v[18:19], v[132:133], v[132:133]
	v_pk_mov_b32 v[16:17], v[132:133], v[132:133]
	v_pk_mov_b32 v[14:15], v[132:133], v[132:133]
	v_pk_mov_b32 v[60:61], v[132:133], v[132:133]
	v_pk_mov_b32 v[58:59], v[132:133], v[132:133]
	v_pk_mov_b32 v[56:57], v[132:133], v[132:133]
	v_pk_mov_b32 v[54:55], v[132:133], v[132:133]
	v_pk_mov_b32 v[44:45], v[132:133], v[132:133]
	v_pk_mov_b32 v[42:43], v[132:133], v[132:133]
	v_pk_mov_b32 v[40:41], v[132:133], v[132:133]
	v_pk_mov_b32 v[38:39], v[132:133], v[132:133]
	v_pk_mov_b32 v[28:29], v[132:133], v[132:133]
	v_pk_mov_b32 v[26:27], v[132:133], v[132:133]
	v_pk_mov_b32 v[24:25], v[132:133], v[132:133]
	v_pk_mov_b32 v[22:23], v[132:133], v[132:133]
	v_pk_mov_b32 v[12:13], v[132:133], v[132:133]
	v_pk_mov_b32 v[10:11], v[132:133], v[132:133]
	v_pk_mov_b32 v[8:9], v[132:133], v[132:133]
	v_pk_mov_b32 v[6:7], v[132:133], v[132:133]
	s_cbranch_vccnz .LBB0_1076
	s_and_b64 s[40:41], s[40:41], exec
	s_cselect_b32 s17, s25, s29
	s_cselect_b32 s40, s24, s28
	s_add_u32 s28, s28, 0x80080
	s_addc_u32 s29, s29, 0
	s_add_u32 s41, s30, 0x100
	v_mov_b32_e32 v6, 0
	s_addc_u32 s62, s31, 0
	s_mov_b32 s30, 0
	v_mov_b32_e32 v7, v6
	v_pk_mov_b32 v[8:9], v[6:7], v[6:7]
	v_pk_mov_b32 v[10:11], v[6:7], v[6:7]
	v_pk_mov_b32 v[12:13], v[6:7], v[6:7]
	v_pk_mov_b32 v[22:23], v[6:7], v[6:7]
	v_pk_mov_b32 v[24:25], v[6:7], v[6:7]
	v_pk_mov_b32 v[26:27], v[6:7], v[6:7]
	v_pk_mov_b32 v[28:29], v[6:7], v[6:7]
	v_pk_mov_b32 v[38:39], v[6:7], v[6:7]
	v_pk_mov_b32 v[40:41], v[6:7], v[6:7]
	v_pk_mov_b32 v[42:43], v[6:7], v[6:7]
	v_pk_mov_b32 v[44:45], v[6:7], v[6:7]
	v_pk_mov_b32 v[54:55], v[6:7], v[6:7]
	v_pk_mov_b32 v[56:57], v[6:7], v[6:7]
	v_pk_mov_b32 v[58:59], v[6:7], v[6:7]
	v_pk_mov_b32 v[60:61], v[6:7], v[6:7]
	v_pk_mov_b32 v[14:15], v[6:7], v[6:7]
	v_pk_mov_b32 v[16:17], v[6:7], v[6:7]
	v_pk_mov_b32 v[18:19], v[6:7], v[6:7]
	v_pk_mov_b32 v[20:21], v[6:7], v[6:7]
	v_pk_mov_b32 v[30:31], v[6:7], v[6:7]
	v_pk_mov_b32 v[32:33], v[6:7], v[6:7]
	v_pk_mov_b32 v[34:35], v[6:7], v[6:7]
	v_pk_mov_b32 v[36:37], v[6:7], v[6:7]
	v_pk_mov_b32 v[46:47], v[6:7], v[6:7]
	v_pk_mov_b32 v[48:49], v[6:7], v[6:7]
	v_pk_mov_b32 v[50:51], v[6:7], v[6:7]
	v_pk_mov_b32 v[52:53], v[6:7], v[6:7]
	v_pk_mov_b32 v[62:63], v[6:7], v[6:7]
	v_pk_mov_b32 v[64:65], v[6:7], v[6:7]
	v_pk_mov_b32 v[66:67], v[6:7], v[6:7]
	v_pk_mov_b32 v[68:69], v[6:7], v[6:7]
	v_pk_mov_b32 v[70:71], v[6:7], v[6:7]
	v_pk_mov_b32 v[72:73], v[6:7], v[6:7]
	v_pk_mov_b32 v[74:75], v[6:7], v[6:7]
	v_pk_mov_b32 v[76:77], v[6:7], v[6:7]
	v_pk_mov_b32 v[86:87], v[6:7], v[6:7]
	v_pk_mov_b32 v[88:89], v[6:7], v[6:7]
	v_pk_mov_b32 v[90:91], v[6:7], v[6:7]
	v_pk_mov_b32 v[92:93], v[6:7], v[6:7]
	v_pk_mov_b32 v[102:103], v[6:7], v[6:7]
	v_pk_mov_b32 v[104:105], v[6:7], v[6:7]
	v_pk_mov_b32 v[106:107], v[6:7], v[6:7]
	v_pk_mov_b32 v[108:109], v[6:7], v[6:7]
	v_pk_mov_b32 v[118:119], v[6:7], v[6:7]
	v_pk_mov_b32 v[120:121], v[6:7], v[6:7]
	v_pk_mov_b32 v[122:123], v[6:7], v[6:7]
	v_pk_mov_b32 v[124:125], v[6:7], v[6:7]
	v_pk_mov_b32 v[78:79], v[6:7], v[6:7]
	v_pk_mov_b32 v[80:81], v[6:7], v[6:7]
	v_pk_mov_b32 v[82:83], v[6:7], v[6:7]
	v_pk_mov_b32 v[84:85], v[6:7], v[6:7]
	v_pk_mov_b32 v[94:95], v[6:7], v[6:7]
	v_pk_mov_b32 v[96:97], v[6:7], v[6:7]
	v_pk_mov_b32 v[98:99], v[6:7], v[6:7]
	v_pk_mov_b32 v[100:101], v[6:7], v[6:7]
	v_pk_mov_b32 v[110:111], v[6:7], v[6:7]
	v_pk_mov_b32 v[112:113], v[6:7], v[6:7]
	v_pk_mov_b32 v[114:115], v[6:7], v[6:7]
	v_pk_mov_b32 v[116:117], v[6:7], v[6:7]
	v_pk_mov_b32 v[126:127], v[6:7], v[6:7]
	v_pk_mov_b32 v[128:129], v[6:7], v[6:7]
	v_pk_mov_b32 v[130:131], v[6:7], v[6:7]
	v_pk_mov_b32 v[132:133], v[6:7], v[6:7]
	v_add_u32_e32 v147, 0x10000, v157
	v_add_u32_e32 v149, 0x14000, v157
	v_add_u32_e32 v152, 0x18000, v157
	v_add_u32_e32 v154, 0x1c000, v157
	v_add_u32_e32 v0, 0x80000, v140
	v_add_u32_e32 v156, 0x80000, v136
	s_cmp_eq_u64 s[14:15], 0
	s_cbranch_scc1 .Lsp_skip_5
	s_setprio 1

; template <class Epi, class Sched, bool ALIGN_EPI = false, bool SP2 = false>
; __device__ __forceinline__ void gemm_phase(PG8_LAS unsigned char* lds, const Gemm g, const Sched& S, const Epi& E, const int wv) {
;     ...
;         const char* nA = has_next ? (const char*)g.A + (size_t)nxt.pm * tstepA + (g.amod ? (size_t)(nxt.pn % g.amod) * K * 2 : (size_t)0) : cA; const char* nB = has_next ? (const char*)g.Bt + (size_t)nxt.pn * tstepB : cB;
;         for (int t = 0; t < nt; t += 2) {
;     ...
; #pragma unroll
;         for (int a = 0; a < 2; ++a)
; #pragma unroll
;             for (int b = 0; b < 2; ++b)
; #pragma unroll
;                 for (int m = 0; m < 4; ++m)
; #pragma unroll
;                     for (int n = 0; n < 2; ++n) acc[a][b][m][n] = (f32x4){0.f, 0.f, 0.f, 0.f};
;         cur = nxt; cA = nA; cB = nB; ++ui;
.LBB0_1384:
	s_and_b64 s[44:45], s[44:45], exec
	s_cselect_b32 s13, s49, s53
	s_cselect_b32 s19, s48, s52
	s_add_u32 s44, s52, 0x40080
	s_addc_u32 s45, s53, 0
	s_add_u32 s54, s54, 0x100
	v_mov_b32_e32 v2, 0
	s_addc_u32 s55, s55, 0
	s_mov_b32 s52, 0
	v_mov_b32_e32 v3, v2
	v_pk_mov_b32 v[4:5], v[2:3], v[2:3]
	v_pk_mov_b32 v[6:7], v[2:3], v[2:3]
	v_pk_mov_b32 v[8:9], v[2:3], v[2:3]
	v_pk_mov_b32 v[18:19], v[2:3], v[2:3]
	v_pk_mov_b32 v[20:21], v[2:3], v[2:3]
	v_pk_mov_b32 v[22:23], v[2:3], v[2:3]
	v_pk_mov_b32 v[24:25], v[2:3], v[2:3]
	v_pk_mov_b32 v[34:35], v[2:3], v[2:3]
	v_pk_mov_b32 v[36:37], v[2:3], v[2:3]
	v_pk_mov_b32 v[38:39], v[2:3], v[2:3]
	v_pk_mov_b32 v[40:41], v[2:3], v[2:3]
	v_pk_mov_b32 v[50:51], v[2:3], v[2:3]
	v_pk_mov_b32 v[52:53], v[2:3], v[2:3]
	v_pk_mov_b32 v[54:55], v[2:3], v[2:3]
	v_pk_mov_b32 v[56:57], v[2:3], v[2:3]
	v_pk_mov_b32 v[10:11], v[2:3], v[2:3]
	v_pk_mov_b32 v[12:13], v[2:3], v[2:3]
	v_pk_mov_b32 v[14:15], v[2:3], v[2:3]
	v_pk_mov_b32 v[16:17], v[2:3], v[2:3]
	v_pk_mov_b32 v[26:27], v[2:3], v[2:3]
	v_pk_mov_b32 v[28:29], v[2:3], v[2:3]
	v_pk_mov_b32 v[30:31], v[2:3], v[2:3]
	v_pk_mov_b32 v[32:33], v[2:3], v[2:3]
	v_pk_mov_b32 v[42:43], v[2:3], v[2:3]
	v_pk_mov_b32 v[44:45], v[2:3], v[2:3]
	v_pk_mov_b32 v[46:47], v[2:3], v[2:3]
	v_pk_mov_b32 v[48:49], v[2:3], v[2:3]
	v_pk_mov_b32 v[58:59], v[2:3], v[2:3]
	v_pk_mov_b32 v[60:61], v[2:3], v[2:3]
	v_pk_mov_b32 v[62:63], v[2:3], v[2:3]
	v_pk_mov_b32 v[64:65], v[2:3], v[2:3]
	v_pk_mov_b32 v[66:67], v[2:3], v[2:3]
	v_pk_mov_b32 v[68:69], v[2:3], v[2:3]
	v_pk_mov_b32 v[70:71], v[2:3], v[2:3]
	v_pk_mov_b32 v[72:73], v[2:3], v[2:3]
	v_pk_mov_b32 v[82:83], v[2:3], v[2:3]
	v_pk_mov_b32 v[84:85], v[2:3], v[2:3]
	v_pk_mov_b32 v[86:87], v[2:3], v[2:3]
	v_pk_mov_b32 v[88:89], v[2:3], v[2:3]
	v_pk_mov_b32 v[98:99], v[2:3], v[2:3]
	v_pk_mov_b32 v[100:101], v[2:3], v[2:3]
	v_pk_mov_b32 v[102:103], v[2:3], v[2:3]
	v_pk_mov_b32 v[104:105], v[2:3], v[2:3]
	v_pk_mov_b32 v[118:119], v[2:3], v[2:3]
	v_pk_mov_b32 v[120:121], v[2:3], v[2:3]
	v_pk_mov_b32 v[122:123], v[2:3], v[2:3]
	v_pk_mov_b32 v[124:125], v[2:3], v[2:3]
	v_pk_mov_b32 v[74:75], v[2:3], v[2:3]
	v_pk_mov_b32 v[76:77], v[2:3], v[2:3]
	v_pk_mov_b32 v[78:79], v[2:3], v[2:3]
	v_pk_mov_b32 v[80:81], v[2:3], v[2:3]
	v_pk_mov_b32 v[90:91], v[2:3], v[2:3]
	v_pk_mov_b32 v[92:93], v[2:3], v[2:3]
	v_pk_mov_b32 v[94:95], v[2:3], v[2:3]
	v_pk_mov_b32 v[96:97], v[2:3], v[2:3]
	v_pk_mov_b32 v[106:107], v[2:3], v[2:3]
	v_pk_mov_b32 v[108:109], v[2:3], v[2:3]
	v_pk_mov_b32 v[110:111], v[2:3], v[2:3]
	v_pk_mov_b32 v[112:113], v[2:3], v[2:3]
	v_pk_mov_b32 v[130:131], v[2:3], v[2:3]
	v_pk_mov_b32 v[132:133], v[2:3], v[2:3]
	v_pk_mov_b32 v[134:135], v[2:3], v[2:3]
	v_pk_mov_b32 v[136:137], v[2:3], v[2:3]
	v_add_u32_e32 v201, 0x10000, v230
	v_add_u32_e32 v203, 0x14000, v230
	v_add_u32_e32 v236, 0x18000, v230
	v_add_u32_e32 v237, 0x1c000, v230
	v_add_u32_e32 v212, 0x40000, v194
	v_add_u32_e32 v213, 0x40000, v196
	s_cmp_eq_u64 s[46:47], 0
	s_cbranch_scc1 .Lsp_skip_6
	s_setprio 1
